# split-phase grid barrier P3->P4: workgroups arrive, run P4's weight copies (kernel inputs only), and only then wait for the release
# speedup vs baseline: 1.0032x; 1.0032x over previous
.LBB0_549:
	s_mov_b32 s100, 0
	s_and_b64 vcc, exec, s[42:43]
	s_mov_b64 s[8:9], 0
	s_cbranch_vccnz .LBB0_551
	v_mbcnt_lo_u32_b32 v0, -1, 0
	v_mbcnt_hi_u32_b32 v0, -1, v0
	s_nop 0
	v_cmp_eq_u32_e32 vcc, 0, v0
	s_and_b64 s[8:9], vcc, exec

.LBB0_569:
	s_or_b64 exec, exec, s[14:15]
	buffer_inv sc1
	v_cvt_f32_u32_e32 v4, v2
	s_waitcnt vmcnt(1)
	v_readfirstlane_b32 s10, v3
	v_sub_u32_e32 v3, 0, v2
	v_rcp_iflag_f32_e32 v4, v4
	v_add_u32_e32 v5, s10, v1
	v_mul_f32_e32 v4, 0x4f7ffffe, v4
	v_cvt_u32_f32_e32 v4, v4
	v_mul_lo_u32 v1, v3, v4
	v_mul_hi_u32 v1, v4, v1
	v_add_u32_e32 v1, v4, v1
	v_mul_hi_u32 v1, v5, v1
	v_mul_lo_u32 v3, v1, v2
	v_sub_u32_e32 v3, v5, v3
	v_add_u32_e32 v4, 1, v1
	v_cmp_ge_u32_e32 vcc, v3, v2
	s_nop 1
	v_cndmask_b32_e32 v1, v1, v4, vcc
	v_sub_u32_e32 v4, v3, v2
	v_cndmask_b32_e32 v3, v3, v4, vcc
	v_add_u32_e32 v4, 1, v1
	v_cmp_ge_u32_e32 vcc, v3, v2
	v_add_u32_e32 v3, 1, v5
	s_nop 0
	v_cndmask_b32_e32 v1, v1, v4, vcc
	v_mul_lo_u32 v4, v2, v1
	v_add_u32_e32 v2, v4, v2
	v_cmp_ne_u32_e32 vcc, v3, v2
	s_and_saveexec_b64 s[10:11], vcc
	s_xor_b64 s[10:11], exec, s[10:11]
	s_cbranch_execz .LBB0_583
	v_readfirstlane_b32 s99, v1
	s_mov_b32 s100, 1

.Lxg_skip_3:
	s_cbranch_vccz .Lsp_glast
	v_readfirstlane_b32 s99, v2
	s_mov_b32 s100, 2
	s_mov_b64 s[10:11], exec
	s_branch .LBB0_600
.Lsp_glast:
	v_mov_b32_e32 v2, 1
	global_atomic_add v[0:1], v2, off
	s_mov_b32 s100, 0
	s_mov_b64 s[10:11], exec

.LBB0_603:
	s_or_b64 exec, exec, s[6:7]
	s_waitcnt lgkmcnt(0)
	v_mbcnt_lo_u32_b32 v234, -1, 0
	v_mbcnt_hi_u32_b32 v234, -1, v234
	s_mov_b32 s98, 0

.Lp4_att_entry:
	s_cmp_eq_u32 s100, 0
	s_cbranch_scc1 .Lsp_done
	s_lshl_b32 s101, s82, 8
	s_add_i32 s101, s101, 0x2400
	s_cmp_eq_u32 s100, 2
	s_cselect_b32 s101, 0x3500, s101
	s_mov_b64 exec, 1
	v_mov_b32_e32 v0, s101
.Lsp_poll:
	global_load_dword v1, v0, s[54:55] sc1
	s_waitcnt vmcnt(0)
	v_readfirstlane_b32 s101, v1
	s_nop 3
	s_cmp_lg_u32 s101, s99
	s_cbranch_scc1 .Lsp_released
	s_sleep 1
	s_branch .Lsp_poll
.Lsp_released:
	s_mov_b64 exec, -1
